# gMLP roles renumbered so each gMLP workgroup reads the h block of its own XCD; with that every h consumer is on the producer's XCD, so norm1's h stores are plain L2 write-back too
# speedup vs baseline: 1.0064x; 1.0064x over previous
.Lnw_skip_n1:
	s_or_b64 exec, exec, s[40:41]
	s_waitcnt vmcnt(36)
	s_barrier
	global_load_dwordx2 v[86:87], v1, s[58:59] offset:0
	global_load_dwordx2 v[90:91], v1, s[58:59] offset:512
	global_load_dwordx2 v[94:95], v1, s[58:59] offset:1024
	global_load_dwordx2 v[98:99], v1, s[58:59] offset:1536
	global_load_dwordx2 v[88:89], v1, s[60:61] offset:0
	global_load_dwordx2 v[92:93], v1, s[60:61] offset:512
	global_load_dwordx2 v[96:97], v1, s[60:61] offset:1024
	global_load_dwordx2 v[100:101], v1, s[60:61] offset:1536
	s_add_u32 s58, s58, 0x800
	s_addc_u32 s59, s59, 0
	s_add_u32 s60, s60, 0x800
	s_addc_u32 s61, s61, 0
	global_load_dwordx2 v[118:119], v1, s[58:59] offset:0
	global_load_dwordx2 v[122:123], v1, s[58:59] offset:512
	global_load_dwordx2 v[134:135], v1, s[58:59] offset:1024
	global_load_dwordx2 v[138:139], v1, s[58:59] offset:1536
	global_load_dwordx2 v[120:121], v1, s[60:61] offset:0
	global_load_dwordx2 v[124:125], v1, s[60:61] offset:512
	global_load_dwordx2 v[136:137], v1, s[60:61] offset:1024
	global_load_dwordx2 v[140:141], v1, s[60:61] offset:1536
	s_add_u32 s58, s58, 0x800
	s_addc_u32 s59, s59, 0
	s_add_u32 s60, s60, 0x800
	s_addc_u32 s61, s61, 0
	global_load_dwordx2 v[172:173], v1, s[58:59] offset:0
	global_load_dwordx2 v[176:177], v1, s[58:59] offset:512
	global_load_dwordx2 v[204:205], v1, s[58:59] offset:1024
	global_load_dwordx2 v[214:215], v1, s[58:59] offset:1536
	global_load_dwordx2 v[174:175], v1, s[60:61] offset:0
	global_load_dwordx2 v[178:179], v1, s[60:61] offset:512
	global_load_dwordx2 v[206:207], v1, s[60:61] offset:1024
	global_load_dwordx2 v[216:217], v1, s[60:61] offset:1536
	s_add_u32 s58, s58, 0x800
	s_addc_u32 s59, s59, 0
	s_add_u32 s60, s60, 0x800
	s_addc_u32 s61, s61, 0
	global_load_dwordx2 v[234:235], v1, s[58:59] offset:0
	global_load_dwordx2 v[238:239], v1, s[58:59] offset:512
	global_load_dwordx2 v[242:243], v1, s[58:59] offset:1024
	global_load_dwordx2 v[246:247], v1, s[58:59] offset:1536
	global_load_dwordx2 v[236:237], v1, s[60:61] offset:0
	global_load_dwordx2 v[240:241], v1, s[60:61] offset:512
	global_load_dwordx2 v[244:245], v1, s[60:61] offset:1024
	global_load_dwordx2 v[248:249], v1, s[60:61] offset:1536
	s_add_u32 s58, s58, 0x800
	s_addc_u32 s59, s59, 0
	s_add_u32 s60, s60, 0x800
	s_addc_u32 s61, s61, 0
	s_waitcnt vmcnt(24)
	v_lshlrev_b32_e32 v14, 16, v86
	v_and_b32_e32 v15, 0xffff0000, v86
	v_lshlrev_b32_e32 v16, 16, v88
	v_and_b32_e32 v17, 0xffff0000, v88
	v_lshlrev_b32_e32 v18, 16, v87
	v_and_b32_e32 v19, 0xffff0000, v87
	v_lshlrev_b32_e32 v20, 16, v89
	v_and_b32_e32 v21, 0xffff0000, v89
	v_pk_add_f32 v[86:87], v[14:15], v[16:17]
	v_pk_add_f32 v[88:89], v[18:19], v[20:21]
	v_lshlrev_b32_e32 v14, 16, v90
	v_and_b32_e32 v15, 0xffff0000, v90
	v_lshlrev_b32_e32 v16, 16, v92
	v_and_b32_e32 v17, 0xffff0000, v92
	v_lshlrev_b32_e32 v18, 16, v91
	v_and_b32_e32 v19, 0xffff0000, v91
	v_lshlrev_b32_e32 v20, 16, v93
	v_and_b32_e32 v21, 0xffff0000, v93
	v_pk_add_f32 v[90:91], v[14:15], v[16:17]
	v_pk_add_f32 v[92:93], v[18:19], v[20:21]
	v_lshlrev_b32_e32 v14, 16, v94
	v_and_b32_e32 v15, 0xffff0000, v94
	v_lshlrev_b32_e32 v16, 16, v96
	v_and_b32_e32 v17, 0xffff0000, v96
	v_lshlrev_b32_e32 v18, 16, v95
	v_and_b32_e32 v19, 0xffff0000, v95
	v_lshlrev_b32_e32 v20, 16, v97
	v_and_b32_e32 v21, 0xffff0000, v97
	v_pk_add_f32 v[94:95], v[14:15], v[16:17]
	v_pk_add_f32 v[96:97], v[18:19], v[20:21]
	v_lshlrev_b32_e32 v14, 16, v98
	v_and_b32_e32 v15, 0xffff0000, v98
	v_lshlrev_b32_e32 v16, 16, v100
	v_and_b32_e32 v17, 0xffff0000, v100
	v_lshlrev_b32_e32 v18, 16, v99
	v_and_b32_e32 v19, 0xffff0000, v99
	v_lshlrev_b32_e32 v20, 16, v101
	v_and_b32_e32 v21, 0xffff0000, v101
	v_pk_add_f32 v[98:99], v[14:15], v[16:17]
	v_pk_add_f32 v[100:101], v[18:19], v[20:21]
	v_pk_mul_f32 v[12:13], v[86:87], v[86:87]
	v_pk_fma_f32 v[12:13], v[88:89], v[88:89], v[12:13]
	v_pk_fma_f32 v[12:13], v[90:91], v[90:91], v[12:13]
	v_pk_fma_f32 v[12:13], v[92:93], v[92:93], v[12:13]
	v_pk_fma_f32 v[12:13], v[94:95], v[94:95], v[12:13]
	v_pk_fma_f32 v[12:13], v[96:97], v[96:97], v[12:13]
	v_pk_fma_f32 v[12:13], v[98:99], v[98:99], v[12:13]
	v_pk_fma_f32 v[12:13], v[100:101], v[100:101], v[12:13]
	v_add_f32_e32 v5, v12, v13
	s_nop 1
	v_add_f32_dpp v5, v5, v5 quad_perm:[1,0,3,2] row_mask:0xf bank_mask:0xf
	s_nop 1
	v_add_f32_dpp v5, v5, v5 quad_perm:[2,3,0,1] row_mask:0xf bank_mask:0xf
	s_nop 1
	v_add_f32_dpp v5, v5, v5 row_half_mirror row_mask:0xf bank_mask:0xf
	s_nop 1
	v_add_f32_dpp v5, v5, v5 row_mirror row_mask:0xf bank_mask:0xf
	s_nop 1
	v_add_f32_dpp v5, v5, v5 row_bcast:15 row_mask:0xa bank_mask:0xf
	s_nop 1
	v_add_f32_dpp v5, v5, v5 row_bcast:31 row_mask:0xc bank_mask:0xf
	s_nop 1
	v_readlane_b32 s32, v5, 63
	s_nop 1
	v_mov_b32_e32 v6, s32
	v_fmamk_f32 v6, v6, 0x3a800000, v146
	v_rsq_f32_e32 v6, v6
	s_nop 0
	v_mul_f32_e32 v8, 0.5, v6
	v_pk_mul_f32 v[14:15], v[86:87], v[8:9] op_sel_hi:[1,0]
	v_pk_fma_f32 v[70:71], v[22:23], v[14:15], v[70:71]
	v_pk_mul_f32 v[14:15], v[88:89], v[8:9] op_sel_hi:[1,0]
	v_pk_fma_f32 v[72:73], v[24:25], v[14:15], v[72:73]
	v_pk_mul_f32 v[14:15], v[90:91], v[8:9] op_sel_hi:[1,0]
	v_pk_fma_f32 v[74:75], v[26:27], v[14:15], v[74:75]
	v_pk_mul_f32 v[14:15], v[92:93], v[8:9] op_sel_hi:[1,0]
	v_pk_fma_f32 v[76:77], v[28:29], v[14:15], v[76:77]
	v_pk_mul_f32 v[14:15], v[94:95], v[8:9] op_sel_hi:[1,0]
	v_pk_fma_f32 v[78:79], v[30:31], v[14:15], v[78:79]
	v_pk_mul_f32 v[14:15], v[96:97], v[8:9] op_sel_hi:[1,0]
	v_pk_fma_f32 v[80:81], v[32:33], v[14:15], v[80:81]
	v_pk_mul_f32 v[14:15], v[98:99], v[8:9] op_sel_hi:[1,0]
	v_pk_fma_f32 v[82:83], v[34:35], v[14:15], v[82:83]
	v_pk_mul_f32 v[14:15], v[100:101], v[8:9] op_sel_hi:[1,0]
	v_pk_fma_f32 v[84:85], v[36:37], v[14:15], v[84:85]
	v_pk_mul_f32 v[12:13], v[70:71], v[70:71]
	v_pk_fma_f32 v[12:13], v[72:73], v[72:73], v[12:13]
	v_pk_fma_f32 v[12:13], v[74:75], v[74:75], v[12:13]
	v_pk_fma_f32 v[12:13], v[76:77], v[76:77], v[12:13]
	v_pk_fma_f32 v[12:13], v[78:79], v[78:79], v[12:13]
	v_pk_fma_f32 v[12:13], v[80:81], v[80:81], v[12:13]
	v_pk_fma_f32 v[12:13], v[82:83], v[82:83], v[12:13]
	v_pk_fma_f32 v[12:13], v[84:85], v[84:85], v[12:13]
	v_add_f32_e32 v5, v12, v13
	s_nop 1
	v_add_f32_dpp v5, v5, v5 quad_perm:[1,0,3,2] row_mask:0xf bank_mask:0xf
	s_nop 1
	v_add_f32_dpp v5, v5, v5 quad_perm:[2,3,0,1] row_mask:0xf bank_mask:0xf
	s_nop 1
	v_add_f32_dpp v5, v5, v5 row_half_mirror row_mask:0xf bank_mask:0xf
	s_nop 1
	v_add_f32_dpp v5, v5, v5 row_mirror row_mask:0xf bank_mask:0xf
	s_nop 1
	v_add_f32_dpp v5, v5, v5 row_bcast:15 row_mask:0xa bank_mask:0xf
	s_nop 1
	v_add_f32_dpp v5, v5, v5 row_bcast:31 row_mask:0xc bank_mask:0xf
	s_nop 1
	v_readlane_b32 s32, v5, 63
	s_nop 1
	v_mov_b32_e32 v6, s32
	v_fmamk_f32 v6, v6, 0x3a800000, v146
	v_rsq_f32_e32 v6, v6
	s_nop 0
	v_mov_b32_e32 v10, v6
	v_pk_mul_f32 v[14:15], v[70:71], v[10:11] op_sel_hi:[1,0]
	v_pk_fma_f32 v[16:17], v[54:55], v[14:15], v[38:39]
	v_pk_mul_f32 v[14:15], v[72:73], v[10:11] op_sel_hi:[1,0]
	v_pk_fma_f32 v[18:19], v[56:57], v[14:15], v[40:41]
	v_cvt_pk_bf16_f32 v86, v16, v17
	v_cvt_pk_bf16_f32 v87, v18, v19
	v_pk_mul_f32 v[14:15], v[74:75], v[10:11] op_sel_hi:[1,0]
	v_pk_fma_f32 v[16:17], v[58:59], v[14:15], v[42:43]
	v_pk_mul_f32 v[14:15], v[76:77], v[10:11] op_sel_hi:[1,0]
	v_pk_fma_f32 v[18:19], v[60:61], v[14:15], v[44:45]
	v_cvt_pk_bf16_f32 v90, v16, v17
	v_cvt_pk_bf16_f32 v91, v18, v19
	v_pk_mul_f32 v[14:15], v[78:79], v[10:11] op_sel_hi:[1,0]
	v_pk_fma_f32 v[16:17], v[62:63], v[14:15], v[46:47]
	v_pk_mul_f32 v[14:15], v[80:81], v[10:11] op_sel_hi:[1,0]
	v_pk_fma_f32 v[18:19], v[64:65], v[14:15], v[48:49]
	v_cvt_pk_bf16_f32 v94, v16, v17
	v_cvt_pk_bf16_f32 v95, v18, v19
	v_pk_mul_f32 v[14:15], v[82:83], v[10:11] op_sel_hi:[1,0]
	v_pk_fma_f32 v[16:17], v[66:67], v[14:15], v[50:51]
	v_pk_mul_f32 v[14:15], v[84:85], v[10:11] op_sel_hi:[1,0]
	v_pk_fma_f32 v[18:19], v[68:69], v[14:15], v[52:53]
	v_cvt_pk_bf16_f32 v98, v16, v17
	v_cvt_pk_bf16_f32 v99, v18, v19
	global_store_dwordx2 v1, v[86:87], s[62:63] offset:0
	global_store_dwordx2 v1, v[90:91], s[62:63] offset:512
	global_store_dwordx2 v1, v[94:95], s[62:63] offset:1024
	global_store_dwordx2 v1, v[98:99], s[62:63] offset:1536
	global_store_dwordx4 v0, v[70:73], s[46:47] offset:0
	global_store_dwordx4 v0, v[74:77], s[46:47] offset:1024
	global_store_dwordx4 v0, v[78:81], s[46:47] offset:2048
	global_store_dwordx4 v0, v[82:85], s[46:47] offset:3072
	s_add_u32 s46, s46, 0x1000
	s_addc_u32 s47, s47, 0
	s_add_u32 s62, s62, 0x800
	s_addc_u32 s63, s63, 0
	s_waitcnt vmcnt(24)
	v_lshlrev_b32_e32 v14, 16, v118
	v_and_b32_e32 v15, 0xffff0000, v118
	v_lshlrev_b32_e32 v16, 16, v120
	v_and_b32_e32 v17, 0xffff0000, v120
	v_lshlrev_b32_e32 v18, 16, v119
	v_and_b32_e32 v19, 0xffff0000, v119
	v_lshlrev_b32_e32 v20, 16, v121
	v_and_b32_e32 v21, 0xffff0000, v121
	v_pk_add_f32 v[118:119], v[14:15], v[16:17]
	v_pk_add_f32 v[120:121], v[18:19], v[20:21]
	v_lshlrev_b32_e32 v14, 16, v122
	v_and_b32_e32 v15, 0xffff0000, v122
	v_lshlrev_b32_e32 v16, 16, v124
	v_and_b32_e32 v17, 0xffff0000, v124
	v_lshlrev_b32_e32 v18, 16, v123
	v_and_b32_e32 v19, 0xffff0000, v123
	v_lshlrev_b32_e32 v20, 16, v125
	v_and_b32_e32 v21, 0xffff0000, v125
	v_pk_add_f32 v[122:123], v[14:15], v[16:17]
	v_pk_add_f32 v[124:125], v[18:19], v[20:21]
	v_lshlrev_b32_e32 v14, 16, v134
	v_and_b32_e32 v15, 0xffff0000, v134
	v_lshlrev_b32_e32 v16, 16, v136
	v_and_b32_e32 v17, 0xffff0000, v136
	v_lshlrev_b32_e32 v18, 16, v135
	v_and_b32_e32 v19, 0xffff0000, v135
	v_lshlrev_b32_e32 v20, 16, v137
	v_and_b32_e32 v21, 0xffff0000, v137
	v_pk_add_f32 v[134:135], v[14:15], v[16:17]
	v_pk_add_f32 v[136:137], v[18:19], v[20:21]
	v_lshlrev_b32_e32 v14, 16, v138
	v_and_b32_e32 v15, 0xffff0000, v138
	v_lshlrev_b32_e32 v16, 16, v140
	v_and_b32_e32 v17, 0xffff0000, v140
	v_lshlrev_b32_e32 v18, 16, v139
	v_and_b32_e32 v19, 0xffff0000, v139
	v_lshlrev_b32_e32 v20, 16, v141
	v_and_b32_e32 v21, 0xffff0000, v141
	v_pk_add_f32 v[138:139], v[14:15], v[16:17]
	v_pk_add_f32 v[140:141], v[18:19], v[20:21]
	v_pk_mul_f32 v[12:13], v[118:119], v[118:119]
	v_pk_fma_f32 v[12:13], v[120:121], v[120:121], v[12:13]
	v_pk_fma_f32 v[12:13], v[122:123], v[122:123], v[12:13]
	v_pk_fma_f32 v[12:13], v[124:125], v[124:125], v[12:13]
	v_pk_fma_f32 v[12:13], v[134:135], v[134:135], v[12:13]
	v_pk_fma_f32 v[12:13], v[136:137], v[136:137], v[12:13]
	v_pk_fma_f32 v[12:13], v[138:139], v[138:139], v[12:13]
	v_pk_fma_f32 v[12:13], v[140:141], v[140:141], v[12:13]
	v_add_f32_e32 v5, v12, v13
	s_nop 1
	v_add_f32_dpp v5, v5, v5 quad_perm:[1,0,3,2] row_mask:0xf bank_mask:0xf
	s_nop 1
	v_add_f32_dpp v5, v5, v5 quad_perm:[2,3,0,1] row_mask:0xf bank_mask:0xf
	s_nop 1
	v_add_f32_dpp v5, v5, v5 row_half_mirror row_mask:0xf bank_mask:0xf
	s_nop 1
	v_add_f32_dpp v5, v5, v5 row_mirror row_mask:0xf bank_mask:0xf
	s_nop 1
	v_add_f32_dpp v5, v5, v5 row_bcast:15 row_mask:0xa bank_mask:0xf
	s_nop 1
	v_add_f32_dpp v5, v5, v5 row_bcast:31 row_mask:0xc bank_mask:0xf
	s_nop 1
	v_readlane_b32 s32, v5, 63
	s_nop 1
	v_mov_b32_e32 v6, s32
	v_fmamk_f32 v6, v6, 0x3a800000, v146
	v_rsq_f32_e32 v6, v6
	s_nop 0
	v_mul_f32_e32 v8, 0.5, v6
	v_pk_mul_f32 v[14:15], v[118:119], v[8:9] op_sel_hi:[1,0]
	v_pk_fma_f32 v[102:103], v[22:23], v[14:15], v[102:103]
	v_pk_mul_f32 v[14:15], v[120:121], v[8:9] op_sel_hi:[1,0]
	v_pk_fma_f32 v[104:105], v[24:25], v[14:15], v[104:105]
	v_pk_mul_f32 v[14:15], v[122:123], v[8:9] op_sel_hi:[1,0]
	v_pk_fma_f32 v[106:107], v[26:27], v[14:15], v[106:107]
	v_pk_mul_f32 v[14:15], v[124:125], v[8:9] op_sel_hi:[1,0]
	v_pk_fma_f32 v[108:109], v[28:29], v[14:15], v[108:109]
	v_pk_mul_f32 v[14:15], v[134:135], v[8:9] op_sel_hi:[1,0]
	v_pk_fma_f32 v[110:111], v[30:31], v[14:15], v[110:111]
	v_pk_mul_f32 v[14:15], v[136:137], v[8:9] op_sel_hi:[1,0]
	v_pk_fma_f32 v[112:113], v[32:33], v[14:15], v[112:113]
	v_pk_mul_f32 v[14:15], v[138:139], v[8:9] op_sel_hi:[1,0]
	v_pk_fma_f32 v[114:115], v[34:35], v[14:15], v[114:115]
	v_pk_mul_f32 v[14:15], v[140:141], v[8:9] op_sel_hi:[1,0]
	v_pk_fma_f32 v[116:117], v[36:37], v[14:15], v[116:117]
	v_pk_mul_f32 v[12:13], v[102:103], v[102:103]
	v_pk_fma_f32 v[12:13], v[104:105], v[104:105], v[12:13]
	v_pk_fma_f32 v[12:13], v[106:107], v[106:107], v[12:13]
	v_pk_fma_f32 v[12:13], v[108:109], v[108:109], v[12:13]
	v_pk_fma_f32 v[12:13], v[110:111], v[110:111], v[12:13]
	v_pk_fma_f32 v[12:13], v[112:113], v[112:113], v[12:13]
	v_pk_fma_f32 v[12:13], v[114:115], v[114:115], v[12:13]
	v_pk_fma_f32 v[12:13], v[116:117], v[116:117], v[12:13]
	v_add_f32_e32 v5, v12, v13
	s_nop 1
	v_add_f32_dpp v5, v5, v5 quad_perm:[1,0,3,2] row_mask:0xf bank_mask:0xf
	s_nop 1
	v_add_f32_dpp v5, v5, v5 quad_perm:[2,3,0,1] row_mask:0xf bank_mask:0xf
	s_nop 1
	v_add_f32_dpp v5, v5, v5 row_half_mirror row_mask:0xf bank_mask:0xf
	s_nop 1
	v_add_f32_dpp v5, v5, v5 row_mirror row_mask:0xf bank_mask:0xf
	s_nop 1
	v_add_f32_dpp v5, v5, v5 row_bcast:15 row_mask:0xa bank_mask:0xf
	s_nop 1
	v_add_f32_dpp v5, v5, v5 row_bcast:31 row_mask:0xc bank_mask:0xf
	s_nop 1
	v_readlane_b32 s32, v5, 63
	s_nop 1
	v_mov_b32_e32 v6, s32
	v_fmamk_f32 v6, v6, 0x3a800000, v146
	v_rsq_f32_e32 v6, v6
	s_nop 0
	v_mov_b32_e32 v10, v6
	v_pk_mul_f32 v[14:15], v[102:103], v[10:11] op_sel_hi:[1,0]
	v_pk_fma_f32 v[16:17], v[54:55], v[14:15], v[38:39]
	v_pk_mul_f32 v[14:15], v[104:105], v[10:11] op_sel_hi:[1,0]
	v_pk_fma_f32 v[18:19], v[56:57], v[14:15], v[40:41]
	v_cvt_pk_bf16_f32 v118, v16, v17
	v_cvt_pk_bf16_f32 v119, v18, v19
	v_pk_mul_f32 v[14:15], v[106:107], v[10:11] op_sel_hi:[1,0]
	v_pk_fma_f32 v[16:17], v[58:59], v[14:15], v[42:43]
	v_pk_mul_f32 v[14:15], v[108:109], v[10:11] op_sel_hi:[1,0]
	v_pk_fma_f32 v[18:19], v[60:61], v[14:15], v[44:45]
	v_cvt_pk_bf16_f32 v122, v16, v17
	v_cvt_pk_bf16_f32 v123, v18, v19
	v_pk_mul_f32 v[14:15], v[110:111], v[10:11] op_sel_hi:[1,0]
	v_pk_fma_f32 v[16:17], v[62:63], v[14:15], v[46:47]
	v_pk_mul_f32 v[14:15], v[112:113], v[10:11] op_sel_hi:[1,0]
	v_pk_fma_f32 v[18:19], v[64:65], v[14:15], v[48:49]
	v_cvt_pk_bf16_f32 v134, v16, v17
	v_cvt_pk_bf16_f32 v135, v18, v19
	v_pk_mul_f32 v[14:15], v[114:115], v[10:11] op_sel_hi:[1,0]
	v_pk_fma_f32 v[16:17], v[66:67], v[14:15], v[50:51]
	v_pk_mul_f32 v[14:15], v[116:117], v[10:11] op_sel_hi:[1,0]
	v_pk_fma_f32 v[18:19], v[68:69], v[14:15], v[52:53]
	v_cvt_pk_bf16_f32 v138, v16, v17
	v_cvt_pk_bf16_f32 v139, v18, v19
	global_store_dwordx2 v1, v[118:119], s[62:63] offset:0
	global_store_dwordx2 v1, v[122:123], s[62:63] offset:512
	global_store_dwordx2 v1, v[134:135], s[62:63] offset:1024
	global_store_dwordx2 v1, v[138:139], s[62:63] offset:1536
	global_store_dwordx4 v0, v[102:105], s[46:47] offset:0
	global_store_dwordx4 v0, v[106:109], s[46:47] offset:1024
	global_store_dwordx4 v0, v[110:113], s[46:47] offset:2048
	global_store_dwordx4 v0, v[114:117], s[46:47] offset:3072
	s_add_u32 s46, s46, 0x1000
	s_addc_u32 s47, s47, 0
	s_add_u32 s62, s62, 0x800
	s_addc_u32 s63, s63, 0
	s_waitcnt vmcnt(24)
	v_lshlrev_b32_e32 v14, 16, v172
	v_and_b32_e32 v15, 0xffff0000, v172
	v_lshlrev_b32_e32 v16, 16, v174
	v_and_b32_e32 v17, 0xffff0000, v174
	v_lshlrev_b32_e32 v18, 16, v173
	v_and_b32_e32 v19, 0xffff0000, v173
	v_lshlrev_b32_e32 v20, 16, v175
	v_and_b32_e32 v21, 0xffff0000, v175
	v_pk_add_f32 v[172:173], v[14:15], v[16:17]
	v_pk_add_f32 v[174:175], v[18:19], v[20:21]
	v_lshlrev_b32_e32 v14, 16, v176
	v_and_b32_e32 v15, 0xffff0000, v176
	v_lshlrev_b32_e32 v16, 16, v178
	v_and_b32_e32 v17, 0xffff0000, v178
	v_lshlrev_b32_e32 v18, 16, v177
	v_and_b32_e32 v19, 0xffff0000, v177
	v_lshlrev_b32_e32 v20, 16, v179
	v_and_b32_e32 v21, 0xffff0000, v179
	v_pk_add_f32 v[176:177], v[14:15], v[16:17]
	v_pk_add_f32 v[178:179], v[18:19], v[20:21]
	v_lshlrev_b32_e32 v14, 16, v204
	v_and_b32_e32 v15, 0xffff0000, v204
	v_lshlrev_b32_e32 v16, 16, v206
	v_and_b32_e32 v17, 0xffff0000, v206
	v_lshlrev_b32_e32 v18, 16, v205
	v_and_b32_e32 v19, 0xffff0000, v205
	v_lshlrev_b32_e32 v20, 16, v207
	v_and_b32_e32 v21, 0xffff0000, v207
	v_pk_add_f32 v[204:205], v[14:15], v[16:17]
	v_pk_add_f32 v[206:207], v[18:19], v[20:21]
	v_lshlrev_b32_e32 v14, 16, v214
	v_and_b32_e32 v15, 0xffff0000, v214
	v_lshlrev_b32_e32 v16, 16, v216
	v_and_b32_e32 v17, 0xffff0000, v216
	v_lshlrev_b32_e32 v18, 16, v215
	v_and_b32_e32 v19, 0xffff0000, v215
	v_lshlrev_b32_e32 v20, 16, v217
	v_and_b32_e32 v21, 0xffff0000, v217
	v_pk_add_f32 v[214:215], v[14:15], v[16:17]
	v_pk_add_f32 v[216:217], v[18:19], v[20:21]
	v_pk_mul_f32 v[12:13], v[172:173], v[172:173]
	v_pk_fma_f32 v[12:13], v[174:175], v[174:175], v[12:13]
	v_pk_fma_f32 v[12:13], v[176:177], v[176:177], v[12:13]
	v_pk_fma_f32 v[12:13], v[178:179], v[178:179], v[12:13]
	v_pk_fma_f32 v[12:13], v[204:205], v[204:205], v[12:13]
	v_pk_fma_f32 v[12:13], v[206:207], v[206:207], v[12:13]
	v_pk_fma_f32 v[12:13], v[214:215], v[214:215], v[12:13]
	v_pk_fma_f32 v[12:13], v[216:217], v[216:217], v[12:13]
	v_add_f32_e32 v5, v12, v13
	s_nop 1
	v_add_f32_dpp v5, v5, v5 quad_perm:[1,0,3,2] row_mask:0xf bank_mask:0xf
	s_nop 1
	v_add_f32_dpp v5, v5, v5 quad_perm:[2,3,0,1] row_mask:0xf bank_mask:0xf
	s_nop 1
	v_add_f32_dpp v5, v5, v5 row_half_mirror row_mask:0xf bank_mask:0xf
	s_nop 1
	v_add_f32_dpp v5, v5, v5 row_mirror row_mask:0xf bank_mask:0xf
	s_nop 1
	v_add_f32_dpp v5, v5, v5 row_bcast:15 row_mask:0xa bank_mask:0xf
	s_nop 1
	v_add_f32_dpp v5, v5, v5 row_bcast:31 row_mask:0xc bank_mask:0xf
	s_nop 1
	v_readlane_b32 s32, v5, 63
	s_nop 1
	v_mov_b32_e32 v6, s32
	v_fmamk_f32 v6, v6, 0x3a800000, v146
	v_rsq_f32_e32 v6, v6
	s_nop 0
	v_mul_f32_e32 v8, 0.5, v6
	v_pk_mul_f32 v[14:15], v[172:173], v[8:9] op_sel_hi:[1,0]
	v_pk_fma_f32 v[154:155], v[22:23], v[14:15], v[154:155]
	v_pk_mul_f32 v[14:15], v[174:175], v[8:9] op_sel_hi:[1,0]
	v_pk_fma_f32 v[156:157], v[24:25], v[14:15], v[156:157]
	v_pk_mul_f32 v[14:15], v[176:177], v[8:9] op_sel_hi:[1,0]
	v_pk_fma_f32 v[158:159], v[26:27], v[14:15], v[158:159]
	v_pk_mul_f32 v[14:15], v[178:179], v[8:9] op_sel_hi:[1,0]
	v_pk_fma_f32 v[160:161], v[28:29], v[14:15], v[160:161]
	v_pk_mul_f32 v[14:15], v[204:205], v[8:9] op_sel_hi:[1,0]
	v_pk_fma_f32 v[162:163], v[30:31], v[14:15], v[162:163]
	v_pk_mul_f32 v[14:15], v[206:207], v[8:9] op_sel_hi:[1,0]
	v_pk_fma_f32 v[164:165], v[32:33], v[14:15], v[164:165]
	v_pk_mul_f32 v[14:15], v[214:215], v[8:9] op_sel_hi:[1,0]
	v_pk_fma_f32 v[168:169], v[34:35], v[14:15], v[168:169]
	v_pk_mul_f32 v[14:15], v[216:217], v[8:9] op_sel_hi:[1,0]
	v_pk_fma_f32 v[170:171], v[36:37], v[14:15], v[170:171]
	v_pk_mul_f32 v[12:13], v[154:155], v[154:155]
	v_pk_fma_f32 v[12:13], v[156:157], v[156:157], v[12:13]
	v_pk_fma_f32 v[12:13], v[158:159], v[158:159], v[12:13]
	v_pk_fma_f32 v[12:13], v[160:161], v[160:161], v[12:13]
	v_pk_fma_f32 v[12:13], v[162:163], v[162:163], v[12:13]
	v_pk_fma_f32 v[12:13], v[164:165], v[164:165], v[12:13]
	v_pk_fma_f32 v[12:13], v[168:169], v[168:169], v[12:13]
	v_pk_fma_f32 v[12:13], v[170:171], v[170:171], v[12:13]
	v_add_f32_e32 v5, v12, v13
	s_nop 1
	v_add_f32_dpp v5, v5, v5 quad_perm:[1,0,3,2] row_mask:0xf bank_mask:0xf
	s_nop 1
	v_add_f32_dpp v5, v5, v5 quad_perm:[2,3,0,1] row_mask:0xf bank_mask:0xf
	s_nop 1
	v_add_f32_dpp v5, v5, v5 row_half_mirror row_mask:0xf bank_mask:0xf
	s_nop 1
	v_add_f32_dpp v5, v5, v5 row_mirror row_mask:0xf bank_mask:0xf
	s_nop 1
	v_add_f32_dpp v5, v5, v5 row_bcast:15 row_mask:0xa bank_mask:0xf
	s_nop 1
	v_add_f32_dpp v5, v5, v5 row_bcast:31 row_mask:0xc bank_mask:0xf
	s_nop 1
	v_readlane_b32 s32, v5, 63
	s_nop 1
	v_mov_b32_e32 v6, s32
	v_fmamk_f32 v6, v6, 0x3a800000, v146
	v_rsq_f32_e32 v6, v6
	s_nop 0
	v_mov_b32_e32 v10, v6
	v_pk_mul_f32 v[14:15], v[154:155], v[10:11] op_sel_hi:[1,0]
	v_pk_fma_f32 v[16:17], v[54:55], v[14:15], v[38:39]
	v_pk_mul_f32 v[14:15], v[156:157], v[10:11] op_sel_hi:[1,0]
	v_pk_fma_f32 v[18:19], v[56:57], v[14:15], v[40:41]
	v_cvt_pk_bf16_f32 v172, v16, v17
	v_cvt_pk_bf16_f32 v173, v18, v19
	v_pk_mul_f32 v[14:15], v[158:159], v[10:11] op_sel_hi:[1,0]
	v_pk_fma_f32 v[16:17], v[58:59], v[14:15], v[42:43]
	v_pk_mul_f32 v[14:15], v[160:161], v[10:11] op_sel_hi:[1,0]
	v_pk_fma_f32 v[18:19], v[60:61], v[14:15], v[44:45]
	v_cvt_pk_bf16_f32 v176, v16, v17
	v_cvt_pk_bf16_f32 v177, v18, v19
	v_pk_mul_f32 v[14:15], v[162:163], v[10:11] op_sel_hi:[1,0]
	v_pk_fma_f32 v[16:17], v[62:63], v[14:15], v[46:47]
	v_pk_mul_f32 v[14:15], v[164:165], v[10:11] op_sel_hi:[1,0]
	v_pk_fma_f32 v[18:19], v[64:65], v[14:15], v[48:49]
	v_cvt_pk_bf16_f32 v204, v16, v17
	v_cvt_pk_bf16_f32 v205, v18, v19
	v_pk_mul_f32 v[14:15], v[168:169], v[10:11] op_sel_hi:[1,0]
	v_pk_fma_f32 v[16:17], v[66:67], v[14:15], v[50:51]
	v_pk_mul_f32 v[14:15], v[170:171], v[10:11] op_sel_hi:[1,0]
	v_pk_fma_f32 v[18:19], v[68:69], v[14:15], v[52:53]
	v_cvt_pk_bf16_f32 v214, v16, v17
	v_cvt_pk_bf16_f32 v215, v18, v19
	global_store_dwordx2 v1, v[172:173], s[62:63] offset:0
	global_store_dwordx2 v1, v[176:177], s[62:63] offset:512
	global_store_dwordx2 v1, v[204:205], s[62:63] offset:1024
	global_store_dwordx2 v1, v[214:215], s[62:63] offset:1536
	global_store_dwordx4 v0, v[154:157], s[46:47] offset:0
	global_store_dwordx4 v0, v[158:161], s[46:47] offset:1024
	global_store_dwordx4 v0, v[162:165], s[46:47] offset:2048
	global_store_dwordx4 v0, v[168:171], s[46:47] offset:3072
	s_add_u32 s46, s46, 0x1000
	s_addc_u32 s47, s47, 0
	s_add_u32 s62, s62, 0x800
	s_addc_u32 s63, s63, 0
	s_waitcnt vmcnt(24)
	v_lshlrev_b32_e32 v14, 16, v234
	v_and_b32_e32 v15, 0xffff0000, v234
	v_lshlrev_b32_e32 v16, 16, v236
	v_and_b32_e32 v17, 0xffff0000, v236
	v_lshlrev_b32_e32 v18, 16, v235
	v_and_b32_e32 v19, 0xffff0000, v235
	v_lshlrev_b32_e32 v20, 16, v237
	v_and_b32_e32 v21, 0xffff0000, v237
	v_pk_add_f32 v[234:235], v[14:15], v[16:17]
	v_pk_add_f32 v[236:237], v[18:19], v[20:21]
	v_lshlrev_b32_e32 v14, 16, v238
	v_and_b32_e32 v15, 0xffff0000, v238
	v_lshlrev_b32_e32 v16, 16, v240
	v_and_b32_e32 v17, 0xffff0000, v240
	v_lshlrev_b32_e32 v18, 16, v239
	v_and_b32_e32 v19, 0xffff0000, v239
	v_lshlrev_b32_e32 v20, 16, v241
	v_and_b32_e32 v21, 0xffff0000, v241
	v_pk_add_f32 v[238:239], v[14:15], v[16:17]
	v_pk_add_f32 v[240:241], v[18:19], v[20:21]
	v_lshlrev_b32_e32 v14, 16, v242
	v_and_b32_e32 v15, 0xffff0000, v242
	v_lshlrev_b32_e32 v16, 16, v244
	v_and_b32_e32 v17, 0xffff0000, v244
	v_lshlrev_b32_e32 v18, 16, v243
	v_and_b32_e32 v19, 0xffff0000, v243
	v_lshlrev_b32_e32 v20, 16, v245
	v_and_b32_e32 v21, 0xffff0000, v245
	v_pk_add_f32 v[242:243], v[14:15], v[16:17]
	v_pk_add_f32 v[244:245], v[18:19], v[20:21]
	v_lshlrev_b32_e32 v14, 16, v246
	v_and_b32_e32 v15, 0xffff0000, v246
	v_lshlrev_b32_e32 v16, 16, v248
	v_and_b32_e32 v17, 0xffff0000, v248
	v_lshlrev_b32_e32 v18, 16, v247
	v_and_b32_e32 v19, 0xffff0000, v247
	v_lshlrev_b32_e32 v20, 16, v249
	v_and_b32_e32 v21, 0xffff0000, v249
	v_pk_add_f32 v[246:247], v[14:15], v[16:17]
	v_pk_add_f32 v[248:249], v[18:19], v[20:21]
	v_pk_mul_f32 v[12:13], v[234:235], v[234:235]
	v_pk_fma_f32 v[12:13], v[236:237], v[236:237], v[12:13]
	v_pk_fma_f32 v[12:13], v[238:239], v[238:239], v[12:13]
	v_pk_fma_f32 v[12:13], v[240:241], v[240:241], v[12:13]
	v_pk_fma_f32 v[12:13], v[242:243], v[242:243], v[12:13]
	v_pk_fma_f32 v[12:13], v[244:245], v[244:245], v[12:13]
	v_pk_fma_f32 v[12:13], v[246:247], v[246:247], v[12:13]
	v_pk_fma_f32 v[12:13], v[248:249], v[248:249], v[12:13]
	v_add_f32_e32 v5, v12, v13
	s_nop 1
	v_add_f32_dpp v5, v5, v5 quad_perm:[1,0,3,2] row_mask:0xf bank_mask:0xf
	s_nop 1
	v_add_f32_dpp v5, v5, v5 quad_perm:[2,3,0,1] row_mask:0xf bank_mask:0xf
	s_nop 1
	v_add_f32_dpp v5, v5, v5 row_half_mirror row_mask:0xf bank_mask:0xf
	s_nop 1
	v_add_f32_dpp v5, v5, v5 row_mirror row_mask:0xf bank_mask:0xf
	s_nop 1
	v_add_f32_dpp v5, v5, v5 row_bcast:15 row_mask:0xa bank_mask:0xf
	s_nop 1
	v_add_f32_dpp v5, v5, v5 row_bcast:31 row_mask:0xc bank_mask:0xf
	s_nop 1
	v_readlane_b32 s32, v5, 63
	s_nop 1
	v_mov_b32_e32 v6, s32
	v_fmamk_f32 v6, v6, 0x3a800000, v146
	v_rsq_f32_e32 v6, v6
	s_nop 0
	v_mul_f32_e32 v8, 0.5, v6
	v_pk_mul_f32 v[14:15], v[234:235], v[8:9] op_sel_hi:[1,0]
	v_pk_fma_f32 v[218:219], v[22:23], v[14:15], v[218:219]
	v_pk_mul_f32 v[14:15], v[236:237], v[8:9] op_sel_hi:[1,0]
	v_pk_fma_f32 v[220:221], v[24:25], v[14:15], v[220:221]
	v_pk_mul_f32 v[14:15], v[238:239], v[8:9] op_sel_hi:[1,0]
	v_pk_fma_f32 v[222:223], v[26:27], v[14:15], v[222:223]
	v_pk_mul_f32 v[14:15], v[240:241], v[8:9] op_sel_hi:[1,0]
	v_pk_fma_f32 v[224:225], v[28:29], v[14:15], v[224:225]
	v_pk_mul_f32 v[14:15], v[242:243], v[8:9] op_sel_hi:[1,0]
	v_pk_fma_f32 v[226:227], v[30:31], v[14:15], v[226:227]
	v_pk_mul_f32 v[14:15], v[244:245], v[8:9] op_sel_hi:[1,0]
	v_pk_fma_f32 v[228:229], v[32:33], v[14:15], v[228:229]
	v_pk_mul_f32 v[14:15], v[246:247], v[8:9] op_sel_hi:[1,0]
	v_pk_fma_f32 v[230:231], v[34:35], v[14:15], v[230:231]
	v_pk_mul_f32 v[14:15], v[248:249], v[8:9] op_sel_hi:[1,0]
	v_pk_fma_f32 v[232:233], v[36:37], v[14:15], v[232:233]
	v_pk_mul_f32 v[12:13], v[218:219], v[218:219]
	v_pk_fma_f32 v[12:13], v[220:221], v[220:221], v[12:13]
	v_pk_fma_f32 v[12:13], v[222:223], v[222:223], v[12:13]
	v_pk_fma_f32 v[12:13], v[224:225], v[224:225], v[12:13]
	v_pk_fma_f32 v[12:13], v[226:227], v[226:227], v[12:13]
	v_pk_fma_f32 v[12:13], v[228:229], v[228:229], v[12:13]
	v_pk_fma_f32 v[12:13], v[230:231], v[230:231], v[12:13]
	v_pk_fma_f32 v[12:13], v[232:233], v[232:233], v[12:13]
	v_add_f32_e32 v5, v12, v13
	s_nop 1
	v_add_f32_dpp v5, v5, v5 quad_perm:[1,0,3,2] row_mask:0xf bank_mask:0xf
	s_nop 1
	v_add_f32_dpp v5, v5, v5 quad_perm:[2,3,0,1] row_mask:0xf bank_mask:0xf
	s_nop 1
	v_add_f32_dpp v5, v5, v5 row_half_mirror row_mask:0xf bank_mask:0xf
	s_nop 1
	v_add_f32_dpp v5, v5, v5 row_mirror row_mask:0xf bank_mask:0xf
	s_nop 1
	v_add_f32_dpp v5, v5, v5 row_bcast:15 row_mask:0xa bank_mask:0xf
	s_nop 1
	v_add_f32_dpp v5, v5, v5 row_bcast:31 row_mask:0xc bank_mask:0xf
	s_nop 1
	v_readlane_b32 s32, v5, 63
	s_nop 1
	v_mov_b32_e32 v6, s32
	v_fmamk_f32 v6, v6, 0x3a800000, v146
	v_rsq_f32_e32 v6, v6
	s_nop 0
	v_mov_b32_e32 v10, v6
	v_pk_mul_f32 v[14:15], v[218:219], v[10:11] op_sel_hi:[1,0]
	v_pk_fma_f32 v[16:17], v[54:55], v[14:15], v[38:39]
	v_pk_mul_f32 v[14:15], v[220:221], v[10:11] op_sel_hi:[1,0]
	v_pk_fma_f32 v[18:19], v[56:57], v[14:15], v[40:41]
	v_cvt_pk_bf16_f32 v234, v16, v17
	v_cvt_pk_bf16_f32 v235, v18, v19
	v_pk_mul_f32 v[14:15], v[222:223], v[10:11] op_sel_hi:[1,0]
	v_pk_fma_f32 v[16:17], v[58:59], v[14:15], v[42:43]
	v_pk_mul_f32 v[14:15], v[224:225], v[10:11] op_sel_hi:[1,0]
	v_pk_fma_f32 v[18:19], v[60:61], v[14:15], v[44:45]
	v_cvt_pk_bf16_f32 v238, v16, v17
	v_cvt_pk_bf16_f32 v239, v18, v19
	v_pk_mul_f32 v[14:15], v[226:227], v[10:11] op_sel_hi:[1,0]
	v_pk_fma_f32 v[16:17], v[62:63], v[14:15], v[46:47]
	v_pk_mul_f32 v[14:15], v[228:229], v[10:11] op_sel_hi:[1,0]
	v_pk_fma_f32 v[18:19], v[64:65], v[14:15], v[48:49]
	v_cvt_pk_bf16_f32 v242, v16, v17
	v_cvt_pk_bf16_f32 v243, v18, v19
	v_pk_mul_f32 v[14:15], v[230:231], v[10:11] op_sel_hi:[1,0]
	v_pk_fma_f32 v[16:17], v[66:67], v[14:15], v[50:51]
	v_pk_mul_f32 v[14:15], v[232:233], v[10:11] op_sel_hi:[1,0]
	v_pk_fma_f32 v[18:19], v[68:69], v[14:15], v[52:53]
	v_cvt_pk_bf16_f32 v246, v16, v17
	v_cvt_pk_bf16_f32 v247, v18, v19
	global_store_dwordx2 v1, v[234:235], s[62:63] offset:0
	global_store_dwordx2 v1, v[238:239], s[62:63] offset:512
	global_store_dwordx2 v1, v[242:243], s[62:63] offset:1024
	global_store_dwordx2 v1, v[246:247], s[62:63] offset:1536
	global_store_dwordx4 v0, v[218:221], s[46:47] offset:0
	global_store_dwordx4 v0, v[222:225], s[46:47] offset:1024
	global_store_dwordx4 v0, v[226:229], s[46:47] offset:2048
	global_store_dwordx4 v0, v[230:233], s[46:47] offset:3072
	s_add_u32 s46, s46, 0x1000
	s_addc_u32 s47, s47, 0
	s_add_u32 s62, s62, 0x800
	s_addc_u32 s63, s63, 0
.LBB0_523:
	s_or_b64 exec, exec, s[8:9]
	v_readfirstlane_b32 s100, v147
	s_nop 0
	s_cmp_eq_u32 s100, 64
	s_cbranch_scc0 .Lei_std_4
	buffer_inv sc1
	s_waitcnt vmcnt(1)
	s_branch .Lei_done_4

.LBB0_939:
	s_or_b64 exec, exec, s[12:13]
	v_cvt_f32_u32_e32 v4, v2
	s_waitcnt vmcnt(0)
	v_readfirstlane_b32 s2, v3
	v_sub_u32_e32 v3, 0, v2
	v_rcp_iflag_f32_e32 v4, v4
	v_add_u32_e32 v5, s2, v1
	v_mul_f32_e32 v4, 0x4f7ffffe, v4
	v_cvt_u32_f32_e32 v4, v4
	v_mul_lo_u32 v1, v3, v4
	v_mul_hi_u32 v1, v4, v1
	v_add_u32_e32 v1, v4, v1
	v_mul_hi_u32 v1, v5, v1
	v_mul_lo_u32 v3, v1, v2
	v_sub_u32_e32 v3, v5, v3
	v_add_u32_e32 v4, 1, v1
	v_cmp_ge_u32_e32 vcc, v3, v2
	s_nop 1
	v_cndmask_b32_e32 v1, v1, v4, vcc
	v_sub_u32_e32 v4, v3, v2
	v_cndmask_b32_e32 v3, v3, v4, vcc
	v_add_u32_e32 v4, 1, v1
	v_cmp_ge_u32_e32 vcc, v3, v2
	v_add_u32_e32 v3, 1, v5
	s_nop 0
	v_cndmask_b32_e32 v1, v1, v4, vcc
	v_mul_lo_u32 v4, v2, v1
	v_add_u32_e32 v2, v4, v2
	v_cmp_ne_u32_e32 vcc, v3, v2
	s_and_saveexec_b64 s[10:11], vcc
	s_xor_b64 s[10:11], exec, s[10:11]
	s_cbranch_execz .LBB0_953
	v_readlane_b32 s18, v255, 0
	s_nop 0
	s_cmp_lt_u32 s18, 0x80
	s_cbranch_scc0 .Lb5_std
	s_bitcmp0_b32 s18, 0
	s_cbranch_scc0 .Lb5_std
	s_bfe_u32 s19, s18, 0x30003
	s_bfe_u32 s18, s18, 0x20001
	s_lshl_b32 s18, s18, 3
	s_or_b32 s18, s18, s19
	s_lshl_b32 s18, s18, 7
	s_add_u32 s18, s18, 0xb000
	v_readlane_b32 s19, v255, 47
	v_mov_b32_e32 v0, s18
	s_mov_b32 s2, 0
	s_waitcnt lgkmcnt(0)

.LBB0_973:
	s_or_b64 exec, exec, s[4:5]
	s_waitcnt lgkmcnt(0)
	s_barrier
	s_load_dwordx2 s[4:5], s[16:17], 0x98
	v_readlane_b32 s2, v255, 0
	s_nop 0
	s_cmp_ge_u32 s2, 0x80
	s_cbranch_scc1 .Lvbx_done
	s_bitcmp1_b32 s2, 0
	s_cbranch_scc1 .Lvbx_odd
	s_bfe_u32 s6, s2, 0x30003
	s_bfe_u32 s7, s2, 0x20001
	s_lshl_b32 s7, s7, 3
	s_or_b32 s6, s6, s7
	s_bfe_u32 s7, s2, 0x10006
	s_lshl_b32 s7, s7, 5
	s_or_b32 s2, s6, s7
	s_branch .Lvbx_done
.Lvbx_odd:
	s_lshr_b32 s2, s2, 1
	s_or_b32 s2, s2, 64
